# FoX prompt tile loop: the wave's LDS-DMA share for tile t+2 is issued after the K-fragment LDS reads (in their latency shadow) instead of before them (on top of v25)
# speedup vs baseline: 1.0037x; 1.0012x over previous
.LBB0_712:
	s_cmp_ge_u32 s71, s94
	s_cselect_b64 s[82:83], -1, 0
	s_mov_b32 s89, s0
	s_sub_i32 s0, s85, 63
	s_cmp_gt_i32 s0, s84
	s_cbranch_scc0 .LBB0_720
	s_and_b64 vcc, exec, s[82:83]
	s_cbranch_vccnz .LBB0_714
	s_lshl_b32 s0, s91, 14
	s_add_i32 s1, s87, s0
	s_add_i32 s0, s92, s0
	s_add_i32 s7, s0, 0x400
	s_mov_b32 m0, s0
	s_add_i32 s6, s1, 0x400
	global_load_lds_dwordx4 v[138:139], off
	s_mov_b32 m0, s7
	v_lshl_add_u64 v[138:139], v[138:139], 0, s[4:5]
	global_load_lds_dwordx4 v[142:143], off
	s_mov_b32 m0, s1
	v_lshl_add_u64 v[142:143], v[142:143], 0, s[4:5]
	global_load_lds_dwordx4 v[140:141], off
	s_mov_b32 m0, s6
	v_lshl_add_u64 v[140:141], v[140:141], 0, s[4:5]
	global_load_lds_dwordx4 v[144:145], off
	v_lshl_add_u64 v[144:145], v[144:145], 0, s[4:5]

.LBB0_720:
	s_lshl_b32 s37, s89, 14
	v_add_u32_e32 v2, s37, v137
	v_add_u32_e32 v3, v2, v146
	ds_read_b128 v[70:73], v3
	ds_read_b128 v[74:77], v3 offset:8192
	v_add_u32_e32 v3, v2, v147
	ds_read_b128 v[160:163], v3
	ds_read_b128 v[164:167], v3 offset:8192
	v_add_u32_e32 v3, v2, v148
	ds_read_b128 v[168:171], v3
	ds_read_b128 v[172:175], v3 offset:8192
	v_add_u32_e32 v3, v2, v149
	ds_read_b128 v[176:179], v3
	ds_read_b128 v[180:183], v3 offset:8192
	v_add_u32_e32 v3, v2, v150
	ds_read_b128 v[184:187], v3
	ds_read_b128 v[188:191], v3 offset:8192
	v_add_u32_e32 v3, v2, v151
	ds_read_b128 v[192:195], v3
	ds_read_b128 v[196:199], v3 offset:8192
	v_add_u32_e32 v3, v2, v152
	v_add_u32_e32 v2, v2, v153
	ds_read_b128 v[200:203], v3
	ds_read_b128 v[204:207], v3 offset:8192
	ds_read_b128 v[208:211], v2
	ds_read_b128 v[216:219], v2 offset:8192
	s_and_b64 vcc, exec, s[82:83]
	s_cbranch_vccnz .Lfoxp_dma_done
	s_lshl_b32 s0, s91, 14
	s_add_i32 s1, s87, s0
	s_add_i32 s0, s92, s0
	s_add_i32 s7, s0, 0x400
	s_mov_b32 m0, s0
	s_add_i32 s6, s1, 0x400
	global_load_lds_dwordx4 v[138:139], off
	s_mov_b32 m0, s7
	v_lshl_add_u64 v[138:139], v[138:139], 0, s[4:5]
	global_load_lds_dwordx4 v[142:143], off
	s_mov_b32 m0, s1
	v_lshl_add_u64 v[142:143], v[142:143], 0, s[4:5]
	global_load_lds_dwordx4 v[140:141], off
	s_mov_b32 m0, s6
	v_lshl_add_u64 v[140:141], v[140:141], 0, s[4:5]
	global_load_lds_dwordx4 v[144:145], off
	v_lshl_add_u64 v[144:145], v[144:145], 0, s[4:5]
.Lfoxp_dma_done:
	s_waitcnt lgkmcnt(8)
	v_mfma_f32_32x32x16_bf16 v[86:101], v[70:73], v[102:105], 0
	v_mfma_f32_32x32x16_bf16 v[70:85], v[74:77], v[102:105], 0
	v_mfma_f32_32x32x16_bf16 v[86:101], v[160:163], v[106:109], v[86:101]
	v_mfma_f32_32x32x16_bf16 v[70:85], v[164:167], v[106:109], v[70:85]
	v_mfma_f32_32x32x16_bf16 v[86:101], v[168:171], v[110:113], v[86:101]
	v_mfma_f32_32x32x16_bf16 v[70:85], v[172:175], v[110:113], v[70:85]
	v_mfma_f32_32x32x16_bf16 v[86:101], v[176:179], v[114:117], v[86:101]
	v_mfma_f32_32x32x16_bf16 v[70:85], v[180:183], v[114:117], v[70:85]
	s_waitcnt lgkmcnt(0)
	v_mfma_f32_32x32x16_bf16 v[86:101], v[184:187], v[118:121], v[86:101]
	v_mfma_f32_32x32x16_bf16 v[70:85], v[188:191], v[118:121], v[70:85]
	v_mfma_f32_32x32x16_bf16 v[86:101], v[192:195], v[122:125], v[86:101]
	v_mfma_f32_32x32x16_bf16 v[70:85], v[196:199], v[122:125], v[70:85]
	v_mfma_f32_32x32x16_bf16 v[86:101], v[200:203], v[126:129], v[86:101]
	v_mfma_f32_32x32x16_bf16 v[70:85], v[204:207], v[126:129], v[70:85]
	v_mfma_f32_32x32x16_bf16 v[86:101], v[208:211], v[130:133], v[86:101]
	v_mfma_f32_32x32x16_bf16 v[70:85], v[216:219], v[130:133], v[70:85]
	v_add_u32_e32 v2, s70, v155
	v_add_u32_e32 v3, 0x1e000, v2
	v_add_u32_e32 v5, 0x1e080, v2
	ds_read_b128 v[160:163], v3
	ds_read_b128 v[164:167], v5
	v_add_u32_e32 v3, 0x1e020, v2
	v_add_u32_e32 v5, 0x1e0a0, v2
	ds_read_b128 v[168:171], v3
	ds_read_b128 v[172:175], v5
	v_add_u32_e32 v3, 0x1e040, v2
	v_add_u32_e32 v5, 0x1e0c0, v2
	ds_read_b128 v[176:179], v3
	ds_read_b128 v[180:183], v5
	v_add_u32_e32 v3, 0x1e060, v2
	v_add_u32_e32 v2, 0x1e0e0, v2
	ds_read_b128 v[184:187], v3
	ds_read_b128 v[188:191], v2
	s_waitcnt lgkmcnt(0)
	v_fma_f32 v2, v100, s86, -v186
	v_fma_f32 v3, v101, s86, -v187
	v_fma_f32 v88, v88, s86, -v162
	v_fma_f32 v89, v89, s86, -v163
	v_fma_f32 v86, v86, s86, -v160
	v_fma_f32 v87, v87, s86, -v161
	v_fma_f32 v98, v98, s86, -v184
	v_fma_f32 v99, v99, s86, -v185
	v_fma_f32 v96, v96, s86, -v178
	v_fma_f32 v97, v97, s86, -v179
	v_fma_f32 v94, v94, s86, -v176
	v_fma_f32 v95, v95, s86, -v177
	v_fma_f32 v92, v92, s86, -v170
	v_fma_f32 v93, v93, s86, -v171
	v_fma_f32 v90, v90, s86, -v168
	v_fma_f32 v91, v91, s86, -v169
	v_fma_f32 v84, v84, s86, -v190
	v_fma_f32 v85, v85, s86, -v191
	v_fma_f32 v82, v82, s86, -v188
	v_fma_f32 v83, v83, s86, -v189
	v_fma_f32 v80, v80, s86, -v182
	v_fma_f32 v81, v81, s86, -v183
	v_fma_f32 v78, v78, s86, -v180
	v_fma_f32 v79, v79, s86, -v181
	v_fma_f32 v76, v76, s86, -v174
	v_fma_f32 v77, v77, s86, -v175
	v_fma_f32 v74, v74, s86, -v172
	v_fma_f32 v75, v75, s86, -v173
	v_fma_f32 v72, v72, s86, -v166
	v_fma_f32 v73, v73, s86, -v167
	s_cmp_le_i32 s85, s95
	v_fma_f32 v70, v70, s86, -v164
	v_fma_f32 v71, v71, s86, -v165
	s_cbranch_scc1 .LBB0_722
	v_cmp_gt_i32_e64 s[66:67], 26, v156
	v_cmp_gt_i32_e64 s[68:69], 27, v156
	v_cmp_gt_i32_e64 s[64:65], 25, v156
	s_and_b64 s[66:67], s[68:69], s[66:67]
	v_cmp_gt_i32_e64 s[62:63], 24, v156
	s_and_b64 s[64:65], s[66:67], s[64:65]
	v_cmp_gt_i32_e64 s[60:61], 19, v156
	s_and_b64 s[62:63], s[64:65], s[62:63]
	v_cmp_gt_i32_e64 s[58:59], 18, v156
	s_and_b64 s[60:61], s[62:63], s[60:61]
	v_cmp_gt_i32_e64 s[56:57], 17, v156
	s_and_b64 s[58:59], s[60:61], s[58:59]
	v_cmp_gt_i32_e64 s[54:55], 16, v156
	s_and_b64 s[56:57], s[58:59], s[56:57]
	v_cmp_gt_i32_e64 s[52:53], 11, v156
	s_and_b64 s[54:55], s[56:57], s[54:55]
	v_cmp_gt_i32_e64 s[50:51], 10, v156
	s_and_b64 s[52:53], s[54:55], s[52:53]
	v_cmp_gt_i32_e64 s[48:49], 9, v156
	s_and_b64 s[50:51], s[52:53], s[50:51]
	v_cmp_gt_i32_e64 s[46:47], 8, v156
	s_and_b64 s[48:49], s[50:51], s[48:49]
	v_cmp_gt_i32_e64 s[44:45], 3, v156
	s_and_b64 s[46:47], s[48:49], s[46:47]
	v_cmp_gt_i32_e64 s[42:43], 2, v156
	s_and_b64 s[44:45], s[46:47], s[44:45]
	v_cmp_gt_i32_e64 s[40:41], 1, v156
	s_and_b64 s[42:43], s[44:45], s[42:43]
	v_cmp_gt_i32_e64 s[0:1], 0, v156
	s_and_b64 s[40:41], s[42:43], s[40:41]
	s_and_b64 s[0:1], s[40:41], s[0:1]
	v_cmp_gt_i32_e64 s[34:35], 58, v156
	v_cndmask_b32_e64 v86, v86, v247, s[0:1]
	v_cmp_gt_i32_e64 s[0:1], 59, v156
	v_cmp_gt_i32_e64 s[30:31], 57, v156
	v_cmp_gt_i32_e64 s[28:29], 56, v156
	v_cndmask_b32_e64 v85, v85, v247, s[0:1]
	s_and_b64 s[0:1], s[0:1], s[34:35]
	v_cndmask_b32_e64 v84, v84, v247, s[0:1]
	s_and_b64 s[0:1], s[0:1], s[30:31]
	v_cmp_gt_i32_e64 s[26:27], 51, v156
	v_cndmask_b32_e64 v83, v83, v247, s[0:1]
	s_and_b64 s[0:1], s[0:1], s[28:29]
	v_cmp_gt_i32_e64 s[24:25], 50, v156
	v_cndmask_b32_e64 v82, v82, v247, s[0:1]
	s_and_b64 s[0:1], s[0:1], s[26:27]
	v_cmp_gt_i32_e64 s[22:23], 49, v156
	v_cndmask_b32_e64 v81, v81, v247, s[0:1]
	s_and_b64 s[0:1], s[0:1], s[24:25]
	v_cmp_gt_i32_e64 s[20:21], 48, v156
	v_cndmask_b32_e64 v80, v80, v247, s[0:1]
	s_and_b64 s[0:1], s[0:1], s[22:23]
	v_cmp_gt_i32_e64 s[18:19], 43, v156
	v_cndmask_b32_e64 v79, v79, v247, s[0:1]
	s_and_b64 s[0:1], s[0:1], s[20:21]
	v_cmp_gt_i32_e64 s[16:17], 42, v156
	v_cndmask_b32_e64 v78, v78, v247, s[0:1]
	s_and_b64 s[0:1], s[0:1], s[18:19]
	v_cmp_gt_i32_e64 s[14:15], 41, v156
	v_cndmask_b32_e64 v77, v77, v247, s[0:1]
	s_and_b64 s[0:1], s[0:1], s[16:17]
	v_cmp_gt_i32_e64 s[12:13], 40, v156
	v_cndmask_b32_e64 v76, v76, v247, s[0:1]
	s_and_b64 s[0:1], s[0:1], s[14:15]
	v_cmp_gt_i32_e64 s[10:11], 35, v156
	v_cndmask_b32_e64 v75, v75, v247, s[0:1]
	s_and_b64 s[0:1], s[0:1], s[12:13]
	v_cmp_gt_i32_e64 s[8:9], 34, v156
	v_cndmask_b32_e64 v74, v74, v247, s[0:1]
	s_and_b64 s[0:1], s[0:1], s[10:11]
	v_cmp_gt_i32_e64 s[6:7], 33, v156
	v_cndmask_b32_e64 v73, v73, v247, s[0:1]
	s_and_b64 s[0:1], s[0:1], s[8:9]
	v_cmp_gt_i32_e32 vcc, 32, v156
	v_cndmask_b32_e64 v72, v72, v247, s[0:1]
	s_and_b64 s[0:1], s[0:1], s[6:7]
	s_and_b64 vcc, s[0:1], vcc
	v_cndmask_b32_e64 v3, v3, v247, s[68:69]
	v_cndmask_b32_e64 v2, v2, v247, s[66:67]
	v_cndmask_b32_e64 v99, v99, v247, s[64:65]
	v_cndmask_b32_e64 v98, v98, v247, s[62:63]
	v_cndmask_b32_e64 v97, v97, v247, s[60:61]
	v_cndmask_b32_e64 v96, v96, v247, s[58:59]
	v_cndmask_b32_e64 v95, v95, v247, s[56:57]
	v_cndmask_b32_e64 v94, v94, v247, s[54:55]
	v_cndmask_b32_e64 v93, v93, v247, s[52:53]
	v_cndmask_b32_e64 v92, v92, v247, s[50:51]
	s_mov_b32 s51, 0x40c000
	v_cndmask_b32_e64 v91, v91, v247, s[48:49]
	s_mov_b64 s[48:49], 0x7ffff
	v_cndmask_b32_e64 v90, v90, v247, s[46:47]
	s_mov_b32 s47, 0x120000
	v_cndmask_b32_e64 v89, v89, v247, s[44:45]
	v_cndmask_b32_e64 v88, v88, v247, s[42:43]
	v_cndmask_b32_e64 v87, v87, v247, s[40:41]
	s_mov_b32 s40, 0x41000000
	v_cndmask_b32_e64 v71, v71, v247, s[0:1]
	v_cndmask_b32_e32 v70, v70, v247, vcc
